# v28_p3epi
# speedup vs baseline: 1.0066x; 1.0066x over previous
; __device__ __forceinline__ float bflo(u32 v) { return __uint_as_float(v << 16); }
; __device__ __forceinline__ float bfhi(u32 v) { return __uint_as_float(v & 0xffff0000u); }
; __device__ void phase3(const Params& p) {
;     ...
;     ACC_BASES;
;     {
;       int koff = 0;
; #pragma unroll
;       for (int ai = 0; ai < 2; ++ai) {
;         asm volatile("" : "+v"(koff), "+v"(rowb), "+v"(colb));
;         u32x4 sb[8];
; #pragma unroll
;         for (int k = 0; k < 8; ++k) sb[k] = __builtin_nontemporal_load((const u32x4*)(gtb + koff + (ai * 8 + k) * 8192));
; #pragma unroll
;         for (int bj = 0; bj < 2; ++bj)
; #pragma unroll
;           for (int m = 0; m < 4; ++m)
; #pragma unroll
;             for (int n = 0; n < 2; ++n) {
;               const u32x4 B4 = sb[bj * 4 + m];
;               u32x2 o;
;               o[0] = pack2(acc[ai][bj][m][n][0] * bflo(B4[2 * n]), acc[ai][bj][m][n][1] * bfhi(B4[2 * n]));
;               o[1] = pack2(acc[ai][bj][m][n][2] * bflo(B4[2 * n + 1]), acc[ai][bj][m][n][3] * bfhi(B4[2 * n + 1]));
;               *(u32x2*)(p.MERGED + (size_t)ACC_ROW * DM + ACC_COL) = o;
;             }
.LBB0_555:
	v_lshl_add_u32 v162, s2, 8, v253
	v_or_b32_e32 v160, s4, v254
	v_mov_b32_e32 v164, 0
	s_mov_b32 s2, 0x20000
	v_ashrrev_i32_e32 v165, 31, v164
	v_lshl_add_u64 v[136:137], v[246:247], 0, v[164:165]
	global_load_dwordx4 v[152:155], v[136:137], off nt
	v_add_co_u32_e32 v128, vcc, 0x2000, v136
	v_ashrrev_i32_e32 v163, 31, v162
	s_nop 0
	v_addc_co_u32_e32 v129, vcc, 0, v137, vcc
	global_load_dwordx4 v[132:135], v[128:129], off nt
	v_add_co_u32_e32 v128, vcc, 0x4000, v136
	v_lshlrev_b64 v[138:139], 13, v[162:163]
	s_nop 0
	v_addc_co_u32_e32 v129, vcc, 0, v137, vcc
	global_load_dwordx4 v[128:131], v[128:129], off nt
	v_ashrrev_i32_e32 v161, 31, v160
	v_lshl_add_u64 v[138:139], s[82:83], 0, v[138:139]
	v_lshl_add_u64 v[168:169], v[160:161], 1, v[138:139]
	v_add_co_u32_e32 v138, vcc, 0x6000, v136
	v_add_co_u32_e64 v170, s[4:5], s2, v168
	s_nop 0
	v_addc_co_u32_e32 v139, vcc, 0, v137, vcc
	global_load_dwordx4 v[156:159], v[138:139], off nt
	v_add_co_u32_e32 v140, vcc, s67, v136
	v_addc_co_u32_e64 v171, s[4:5], 0, v169, s[4:5]
	s_nop 0
	v_addc_co_u32_e32 v141, vcc, 0, v137, vcc
	v_add_co_u32_e32 v138, vcc, s72, v136
	v_lshl_add_u64 v[166:167], v[168:169], 0, s[30:31]
	s_nop 0
	v_addc_co_u32_e32 v139, vcc, 0, v137, vcc
	global_load_dwordx4 v[148:151], v[140:141], off nt
	global_load_dwordx4 v[144:147], v[138:139], off nt
	v_add_co_u32_e32 v142, vcc, s81, v136
	s_mov_b32 s2, 0x40000
	s_nop 0
	v_addc_co_u32_e32 v143, vcc, 0, v137, vcc
	v_add_co_u32_e32 v136, vcc, s84, v136
	s_mov_b64 s[4:5], 0x40000
	s_nop 0
	v_addc_co_u32_e32 v137, vcc, 0, v137, vcc
	global_load_dwordx4 v[140:143], v[142:143], off nt
	s_nop 0
	global_load_dwordx4 v[136:139], v[136:137], off nt
	s_mov_b32 s101, 0
	v_lshl_add_u64 v[224:225], v[246:247], 0, v[164:165]
	s_mov_b32 s100, s75
	v_lshl_add_u64 v[226:227], v[224:225], 0, s[100:101]
	global_load_dwordx4 v[192:195], v[226:227], off nt
	s_mov_b32 s100, s85
	v_lshl_add_u64 v[226:227], v[224:225], 0, s[100:101]
	global_load_dwordx4 v[196:199], v[226:227], off nt
	s_mov_b32 s100, s80
	v_lshl_add_u64 v[226:227], v[224:225], 0, s[100:101]
	global_load_dwordx4 v[200:203], v[226:227], off nt
	s_mov_b32 s100, s86
	v_lshl_add_u64 v[226:227], v[224:225], 0, s[100:101]
	global_load_dwordx4 v[204:207], v[226:227], off nt
	s_mov_b32 s100, s65
	v_lshl_add_u64 v[226:227], v[224:225], 0, s[100:101]
	global_load_dwordx4 v[208:211], v[226:227], off nt
	s_mov_b32 s100, s66
	v_lshl_add_u64 v[226:227], v[224:225], 0, s[100:101]
	global_load_dwordx4 v[212:215], v[226:227], off nt
	s_mov_b32 s100, s73
	v_lshl_add_u64 v[226:227], v[224:225], 0, s[100:101]
	global_load_dwordx4 v[216:219], v[226:227], off nt
	s_mov_b32 s100, s74
	v_lshl_add_u64 v[226:227], v[224:225], 0, s[100:101]
	global_load_dwordx4 v[220:223], v[226:227], off nt
	s_nop 0
	s_waitcnt vmcnt(14)
	v_lshlrev_b32_e32 v172, 16, v152
	v_and_b32_e32 v173, 0xffff0000, v152
	v_lshlrev_b32_e32 v152, 16, v153
	v_and_b32_e32 v153, 0xffff0000, v153
	v_lshlrev_b32_e32 v174, 16, v154
	v_and_b32_e32 v175, 0xffff0000, v154
	v_lshlrev_b32_e32 v154, 16, v155
	v_and_b32_e32 v155, 0xffff0000, v155
	v_pk_mul_f32 v[120:121], v[120:121], v[172:173]
	v_pk_mul_f32 v[122:123], v[122:123], v[152:153]
	v_pk_mul_f32 v[124:125], v[124:125], v[174:175]
	v_pk_mul_f32 v[126:127], v[126:127], v[154:155]
	v_cvt_pk_bf16_f32 v120, v120, v121
	v_cvt_pk_bf16_f32 v121, v122, v123
	v_cvt_pk_bf16_f32 v122, v124, v125
	v_cvt_pk_bf16_f32 v123, v126, v127
	v_lshlrev_b32_e32 v124, 16, v132
	v_and_b32_e32 v125, 0xffff0000, v132
	v_lshlrev_b32_e32 v126, 16, v133
	v_and_b32_e32 v127, 0xffff0000, v133
	v_pk_mul_f32 v[116:117], v[116:117], v[124:125]
	v_pk_mul_f32 v[118:119], v[118:119], v[126:127]
	v_cvt_pk_bf16_f32 v116, v116, v117
	v_cvt_pk_bf16_f32 v117, v118, v119
	v_lshlrev_b32_e32 v132, 16, v134
	v_and_b32_e32 v133, 0xffff0000, v134
	global_store_dwordx2 v[168:169], v[120:121], off
	global_store_dwordx2 v[168:169], v[122:123], off offset:32
	global_store_dwordx2 v[170:171], v[116:117], off
	v_lshlrev_b32_e32 v116, 16, v135
	v_and_b32_e32 v117, 0xffff0000, v135
	v_pk_mul_f32 v[112:113], v[112:113], v[132:133]
	v_pk_mul_f32 v[114:115], v[114:115], v[116:117]
	v_cvt_pk_bf16_f32 v112, v112, v113
	v_cvt_pk_bf16_f32 v113, v114, v115
	global_store_dwordx2 v[166:167], v[112:113], off offset:32
	s_waitcnt vmcnt(17)
	v_lshlrev_b32_e32 v112, 16, v128
	v_and_b32_e32 v113, 0xffff0000, v128
	v_pk_mul_f32 v[108:109], v[108:109], v[112:113]
	v_lshlrev_b32_e32 v112, 16, v129
	v_and_b32_e32 v113, 0xffff0000, v129
	v_pk_mul_f32 v[110:111], v[110:111], v[112:113]
	v_add_co_u32_e32 v112, vcc, s2, v168
	v_cvt_pk_bf16_f32 v108, v108, v109
	v_cvt_pk_bf16_f32 v109, v110, v111
	v_addc_co_u32_e32 v113, vcc, 0, v169, vcc
	global_store_dwordx2 v[112:113], v[108:109], off
	v_lshlrev_b32_e32 v108, 16, v130
	v_and_b32_e32 v109, 0xffff0000, v130
	v_pk_mul_f32 v[104:105], v[104:105], v[108:109]
	v_lshlrev_b32_e32 v108, 16, v131
	v_and_b32_e32 v109, 0xffff0000, v131
	v_pk_mul_f32 v[106:107], v[106:107], v[108:109]
	v_lshl_add_u64 v[110:111], v[168:169], 0, s[4:5]
	v_cvt_pk_bf16_f32 v104, v104, v105
	v_cvt_pk_bf16_f32 v105, v106, v107
	global_store_dwordx2 v[110:111], v[104:105], off offset:32
	s_waitcnt vmcnt(18)
; __device__ __forceinline__ float bflo(u32 v) { return __uint_as_float(v << 16); }
; __device__ __forceinline__ float bfhi(u32 v) { return __uint_as_float(v & 0xffff0000u); }
; __device__ void phase3(const Params& p) {
;     ...
;         for (int k = 0; k < 8; ++k) sb[k] = __builtin_nontemporal_load((const u32x4*)(gtb + koff + (ai * 8 + k) * 8192));
; #pragma unroll
;         for (int bj = 0; bj < 2; ++bj)
; #pragma unroll
;           for (int m = 0; m < 4; ++m)
; #pragma unroll
;             for (int n = 0; n < 2; ++n) {
;               const u32x4 B4 = sb[bj * 4 + m];
;               u32x2 o;
;               o[0] = pack2(acc[ai][bj][m][n][0] * bflo(B4[2 * n]), acc[ai][bj][m][n][1] * bfhi(B4[2 * n]));
;               o[1] = pack2(acc[ai][bj][m][n][2] * bflo(B4[2 * n + 1]), acc[ai][bj][m][n][3] * bfhi(B4[2 * n + 1]));
;               *(u32x2*)(p.MERGED + (size_t)ACC_ROW * DM + ACC_COL) = o;
;             }
	v_lshlrev_b32_e32 v104, 16, v156
	v_and_b32_e32 v105, 0xffff0000, v156
	v_pk_mul_f32 v[100:101], v[100:101], v[104:105]
	v_lshlrev_b32_e32 v104, 16, v157
	v_and_b32_e32 v105, 0xffff0000, v157
	s_mov_b32 s2, 0x60000
	v_pk_mul_f32 v[102:103], v[102:103], v[104:105]
	v_add_co_u32_e32 v104, vcc, s2, v168
	v_cvt_pk_bf16_f32 v100, v100, v101
	v_cvt_pk_bf16_f32 v101, v102, v103
	v_addc_co_u32_e32 v105, vcc, 0, v169, vcc
	global_store_dwordx2 v[104:105], v[100:101], off
	v_lshlrev_b32_e32 v100, 16, v158
	v_and_b32_e32 v101, 0xffff0000, v158
	v_pk_mul_f32 v[96:97], v[96:97], v[100:101]
	v_lshlrev_b32_e32 v100, 16, v159
	v_and_b32_e32 v101, 0xffff0000, v159
	s_mov_b64 s[4:5], 0x60000
	v_pk_mul_f32 v[98:99], v[98:99], v[100:101]
	v_lshl_add_u64 v[102:103], v[168:169], 0, s[4:5]
	v_cvt_pk_bf16_f32 v96, v96, v97
	v_cvt_pk_bf16_f32 v97, v98, v99
	global_store_dwordx2 v[102:103], v[96:97], off offset:32
	s_waitcnt vmcnt(19)
	v_lshlrev_b32_e32 v96, 16, v148
	v_and_b32_e32 v97, 0xffff0000, v148
	v_pk_mul_f32 v[92:93], v[92:93], v[96:97]
	v_lshlrev_b32_e32 v96, 16, v149
	v_and_b32_e32 v97, 0xffff0000, v149
	v_pk_mul_f32 v[94:95], v[94:95], v[96:97]
	v_cvt_pk_bf16_f32 v92, v92, v93
	v_cvt_pk_bf16_f32 v93, v94, v95
	global_store_dwordx2 v[168:169], v[92:93], off offset:256
	v_lshlrev_b32_e32 v92, 16, v150
	v_and_b32_e32 v93, 0xffff0000, v150
	v_pk_mul_f32 v[88:89], v[88:89], v[92:93]
	v_lshlrev_b32_e32 v92, 16, v151
	v_and_b32_e32 v93, 0xffff0000, v151
	v_pk_mul_f32 v[90:91], v[90:91], v[92:93]
	v_cvt_pk_bf16_f32 v88, v88, v89
	v_cvt_pk_bf16_f32 v89, v90, v91
	global_store_dwordx2 v[168:169], v[88:89], off offset:288
	s_waitcnt vmcnt(20)
	v_lshlrev_b32_e32 v88, 16, v144
	v_and_b32_e32 v89, 0xffff0000, v144
	v_pk_mul_f32 v[84:85], v[84:85], v[88:89]
	v_lshlrev_b32_e32 v88, 16, v145
	v_and_b32_e32 v89, 0xffff0000, v145
	v_pk_mul_f32 v[86:87], v[86:87], v[88:89]
	v_cvt_pk_bf16_f32 v84, v84, v85
	v_cvt_pk_bf16_f32 v85, v86, v87
	global_store_dwordx2 v[166:167], v[84:85], off offset:256
	v_lshlrev_b32_e32 v84, 16, v146
	v_and_b32_e32 v85, 0xffff0000, v146
	v_pk_mul_f32 v[80:81], v[80:81], v[84:85]
	v_lshlrev_b32_e32 v84, 16, v147
	v_and_b32_e32 v85, 0xffff0000, v147
	v_pk_mul_f32 v[82:83], v[82:83], v[84:85]
	v_cvt_pk_bf16_f32 v80, v80, v81
	v_cvt_pk_bf16_f32 v81, v82, v83
	global_store_dwordx2 v[166:167], v[80:81], off offset:288
	s_waitcnt vmcnt(21)
	v_lshlrev_b32_e32 v80, 16, v140
	v_and_b32_e32 v81, 0xffff0000, v140
	v_pk_mul_f32 v[76:77], v[76:77], v[80:81]
	v_lshlrev_b32_e32 v80, 16, v141
	v_and_b32_e32 v81, 0xffff0000, v141
	v_pk_mul_f32 v[78:79], v[78:79], v[80:81]
	v_cvt_pk_bf16_f32 v76, v76, v77
	v_cvt_pk_bf16_f32 v77, v78, v79
	global_store_dwordx2 v[110:111], v[76:77], off offset:256
	v_lshlrev_b32_e32 v76, 16, v142
	v_and_b32_e32 v77, 0xffff0000, v142
	v_pk_mul_f32 v[72:73], v[72:73], v[76:77]
	v_lshlrev_b32_e32 v76, 16, v143
	v_and_b32_e32 v77, 0xffff0000, v143
	v_pk_mul_f32 v[74:75], v[74:75], v[76:77]
	v_cvt_pk_bf16_f32 v72, v72, v73
	v_cvt_pk_bf16_f32 v73, v74, v75
	global_store_dwordx2 v[110:111], v[72:73], off offset:288
	s_waitcnt vmcnt(22)
	v_lshlrev_b32_e32 v72, 16, v136
	v_and_b32_e32 v73, 0xffff0000, v136
	v_pk_mul_f32 v[68:69], v[68:69], v[72:73]
	v_lshlrev_b32_e32 v72, 16, v137
	v_and_b32_e32 v73, 0xffff0000, v137
	v_pk_mul_f32 v[70:71], v[70:71], v[72:73]
	v_cvt_pk_bf16_f32 v68, v68, v69
	v_cvt_pk_bf16_f32 v69, v70, v71
	global_store_dwordx2 v[102:103], v[68:69], off offset:256
	v_lshlrev_b32_e32 v68, 16, v138
	v_and_b32_e32 v69, 0xffff0000, v138
	v_pk_mul_f32 v[64:65], v[64:65], v[68:69]
	v_lshlrev_b32_e32 v68, 16, v139
	v_and_b32_e32 v69, 0xffff0000, v139
	v_pk_mul_f32 v[66:67], v[66:67], v[68:69]
	v_cvt_pk_bf16_f32 v64, v64, v65
	v_cvt_pk_bf16_f32 v65, v66, v67
	global_store_dwordx2 v[102:103], v[64:65], off offset:288
	s_waitcnt vmcnt(22)
	s_mov_b32 s2, 0x100000
	v_ashrrev_i32_e32 v165, 31, v164
	v_lshl_add_u64 v[68:69], v[246:247], 0, v[164:165]
	v_add_co_u32_e32 v64, vcc, s75, v68
	v_ashrrev_i32_e32 v163, 31, v162
	s_nop 0
	v_addc_co_u32_e32 v65, vcc, 0, v69, vcc
	v_add_co_u32_e32 v64, vcc, s85, v68
	v_ashrrev_i32_e32 v161, 31, v160
	s_nop 0
	v_addc_co_u32_e32 v65, vcc, 0, v69, vcc
	v_add_co_u32_e32 v70, vcc, s80, v68
	s_mov_b64 s[4:5], 0x100000
	s_nop 0
	v_addc_co_u32_e32 v71, vcc, 0, v69, vcc
	v_add_co_u32_e32 v72, vcc, s86, v68
	v_lshlrev_b64 v[70:71], 13, v[162:163]
	s_nop 0
	v_addc_co_u32_e32 v73, vcc, 0, v69, vcc
	v_add_co_u32_e32 v74, vcc, s65, v68
	v_lshl_add_u64 v[98:99], s[82:83], 0, v[70:71]
	s_nop 0
	v_addc_co_u32_e32 v75, vcc, 0, v69, vcc
	v_add_co_u32_e32 v84, vcc, s66, v68
	v_lshl_add_u64 v[98:99], v[160:161], 1, v[98:99]
	s_nop 0
	v_addc_co_u32_e32 v85, vcc, 0, v69, vcc
	v_add_co_u32_e32 v88, vcc, s73, v68
	s_mov_b32 s11, 0x120000
	s_nop 0
	v_addc_co_u32_e32 v89, vcc, 0, v69, vcc
	v_add_co_u32_e32 v68, vcc, s74, v68
	v_lshl_add_u64 v[100:101], v[98:99], 0, s[4:5]
	s_nop 0
	v_addc_co_u32_e32 v69, vcc, 0, v69, vcc
	s_nop 0
	s_nop 0
	s_nop 0
	v_add_co_u32_e32 v102, vcc, s2, v98
	s_mov_b64 s[48:49], 0x120000
	s_nop 0
	v_addc_co_u32_e32 v103, vcc, 0, v99, vcc
	v_lshl_add_u64 v[88:89], v[98:99], 0, s[48:49]
	s_mov_b64 s[4:5], 0x140000
	s_nop 0
	v_lshlrev_b32_e32 v104, 16, v192
	v_and_b32_e32 v105, 0xffff0000, v192
	v_lshlrev_b32_e32 v76, 16, v193
	v_and_b32_e32 v77, 0xffff0000, v193
	v_lshlrev_b32_e32 v106, 16, v194
	v_and_b32_e32 v107, 0xffff0000, v194
	v_lshlrev_b32_e32 v78, 16, v195
	v_and_b32_e32 v79, 0xffff0000, v195
	v_pk_mul_f32 v[52:53], v[52:53], v[104:105]
	v_pk_mul_f32 v[54:55], v[54:55], v[76:77]
	v_lshlrev_b32_e32 v108, 16, v196
	v_and_b32_e32 v109, 0xffff0000, v196
	v_lshlrev_b32_e32 v64, 16, v197
	v_and_b32_e32 v65, 0xffff0000, v197
	v_pk_mul_f32 v[56:57], v[56:57], v[106:107]
	v_pk_mul_f32 v[58:59], v[58:59], v[78:79]
	v_cvt_pk_bf16_f32 v52, v52, v53
	v_cvt_pk_bf16_f32 v53, v54, v55
	v_pk_mul_f32 v[60:61], v[60:61], v[108:109]
	v_pk_mul_f32 v[62:63], v[62:63], v[64:65]
	v_cvt_pk_bf16_f32 v54, v56, v57
	v_cvt_pk_bf16_f32 v55, v58, v59
	global_store_dwordx2 v[102:103], v[52:53], off
	global_store_dwordx2 v[100:101], v[54:55], off offset:32
	v_add_co_u32_e32 v52, vcc, s11, v98
	v_cvt_pk_bf16_f32 v56, v60, v61
	v_cvt_pk_bf16_f32 v57, v62, v63
	v_addc_co_u32_e32 v53, vcc, 0, v99, vcc
	global_store_dwordx2 v[52:53], v[56:57], off
	v_lshlrev_b32_e32 v52, 16, v198
	v_and_b32_e32 v53, 0xffff0000, v198
	v_pk_mul_f32 v[48:49], v[48:49], v[52:53]
	v_lshlrev_b32_e32 v52, 16, v199
	v_and_b32_e32 v53, 0xffff0000, v199
	v_pk_mul_f32 v[50:51], v[50:51], v[52:53]
	v_cvt_pk_bf16_f32 v48, v48, v49
	v_cvt_pk_bf16_f32 v49, v50, v51
	global_store_dwordx2 v[88:89], v[48:49], off offset:32
	s_waitcnt vmcnt(25)
; __device__ __forceinline__ float bflo(u32 v) { return __uint_as_float(v << 16); }
; __device__ __forceinline__ float bfhi(u32 v) { return __uint_as_float(v & 0xffff0000u); }
; __device__ void phase3(const Params& p) {
;     ...
;   for (int t = blockIdx.x; t < 1024; t += gridDim.x) {
;     ...
;         for (int k = 0; k < 8; ++k) sb[k] = __builtin_nontemporal_load((const u32x4*)(gtb + koff + (ai * 8 + k) * 8192));
; #pragma unroll
;         for (int bj = 0; bj < 2; ++bj)
; #pragma unroll
;           for (int m = 0; m < 4; ++m)
; #pragma unroll
;             for (int n = 0; n < 2; ++n) {
;               const u32x4 B4 = sb[bj * 4 + m];
;               u32x2 o;
;               o[0] = pack2(acc[ai][bj][m][n][0] * bflo(B4[2 * n]), acc[ai][bj][m][n][1] * bfhi(B4[2 * n]));
;               o[1] = pack2(acc[ai][bj][m][n][2] * bflo(B4[2 * n + 1]), acc[ai][bj][m][n][3] * bfhi(B4[2 * n + 1]));
;               *(u32x2*)(p.MERGED + (size_t)ACC_ROW * DM + ACC_COL) = o;
;             }
	v_lshlrev_b32_e32 v48, 16, v200
	v_and_b32_e32 v49, 0xffff0000, v200
	v_pk_mul_f32 v[44:45], v[44:45], v[48:49]
	v_lshlrev_b32_e32 v48, 16, v201
	v_and_b32_e32 v49, 0xffff0000, v201
	v_pk_mul_f32 v[46:47], v[46:47], v[48:49]
	v_add_co_u32_e32 v48, vcc, s90, v98
	v_cvt_pk_bf16_f32 v44, v44, v45
	v_cvt_pk_bf16_f32 v45, v46, v47
	v_addc_co_u32_e32 v49, vcc, 0, v99, vcc
	global_store_dwordx2 v[48:49], v[44:45], off
	v_lshlrev_b32_e32 v44, 16, v202
	v_and_b32_e32 v45, 0xffff0000, v202
	v_pk_mul_f32 v[40:41], v[40:41], v[44:45]
	v_lshlrev_b32_e32 v44, 16, v203
	v_and_b32_e32 v45, 0xffff0000, v203
	v_pk_mul_f32 v[42:43], v[42:43], v[44:45]
	v_lshl_add_u64 v[46:47], v[98:99], 0, s[4:5]
	v_cvt_pk_bf16_f32 v40, v40, v41
	v_cvt_pk_bf16_f32 v41, v42, v43
	global_store_dwordx2 v[46:47], v[40:41], off offset:32
	s_waitcnt vmcnt(26)
	v_lshlrev_b32_e32 v40, 16, v204
	v_and_b32_e32 v41, 0xffff0000, v204
	v_pk_mul_f32 v[36:37], v[36:37], v[40:41]
	v_lshlrev_b32_e32 v40, 16, v205
	v_and_b32_e32 v41, 0xffff0000, v205
	v_pk_mul_f32 v[38:39], v[38:39], v[40:41]
	v_add_co_u32_e32 v40, vcc, s91, v98
	v_cvt_pk_bf16_f32 v36, v36, v37
	v_cvt_pk_bf16_f32 v37, v38, v39
	v_addc_co_u32_e32 v41, vcc, 0, v99, vcc
	global_store_dwordx2 v[40:41], v[36:37], off
	v_lshlrev_b32_e32 v36, 16, v206
	v_and_b32_e32 v37, 0xffff0000, v206
	v_pk_mul_f32 v[32:33], v[32:33], v[36:37]
	v_lshlrev_b32_e32 v36, 16, v207
	v_and_b32_e32 v37, 0xffff0000, v207
	v_pk_mul_f32 v[34:35], v[34:35], v[36:37]
	v_lshl_add_u64 v[38:39], v[98:99], 0, s[42:43]
	v_cvt_pk_bf16_f32 v32, v32, v33
	v_cvt_pk_bf16_f32 v33, v34, v35
	global_store_dwordx2 v[38:39], v[32:33], off offset:32
	s_waitcnt vmcnt(27)
	v_lshlrev_b32_e32 v32, 16, v208
	v_and_b32_e32 v33, 0xffff0000, v208
	v_pk_mul_f32 v[28:29], v[28:29], v[32:33]
	v_lshlrev_b32_e32 v32, 16, v209
	v_and_b32_e32 v33, 0xffff0000, v209
	v_pk_mul_f32 v[30:31], v[30:31], v[32:33]
	v_cvt_pk_bf16_f32 v28, v28, v29
	v_cvt_pk_bf16_f32 v29, v30, v31
	global_store_dwordx2 v[100:101], v[28:29], off offset:256
	v_lshlrev_b32_e32 v28, 16, v210
	v_and_b32_e32 v29, 0xffff0000, v210
	v_pk_mul_f32 v[24:25], v[24:25], v[28:29]
	v_lshlrev_b32_e32 v28, 16, v211
	v_and_b32_e32 v29, 0xffff0000, v211
	v_pk_mul_f32 v[26:27], v[26:27], v[28:29]
	v_cvt_pk_bf16_f32 v24, v24, v25
	v_cvt_pk_bf16_f32 v25, v26, v27
	global_store_dwordx2 v[100:101], v[24:25], off offset:288
	s_waitcnt vmcnt(28)
	v_lshlrev_b32_e32 v24, 16, v212
	v_and_b32_e32 v25, 0xffff0000, v212
	v_pk_mul_f32 v[20:21], v[20:21], v[24:25]
	v_lshlrev_b32_e32 v24, 16, v213
	v_and_b32_e32 v25, 0xffff0000, v213
	v_pk_mul_f32 v[22:23], v[22:23], v[24:25]
	v_cvt_pk_bf16_f32 v20, v20, v21
	v_cvt_pk_bf16_f32 v21, v22, v23
	global_store_dwordx2 v[88:89], v[20:21], off offset:256
	v_lshlrev_b32_e32 v20, 16, v214
	v_and_b32_e32 v21, 0xffff0000, v214
	v_pk_mul_f32 v[16:17], v[16:17], v[20:21]
	v_lshlrev_b32_e32 v20, 16, v215
	v_and_b32_e32 v21, 0xffff0000, v215
	v_pk_mul_f32 v[18:19], v[18:19], v[20:21]
	v_cvt_pk_bf16_f32 v16, v16, v17
	v_cvt_pk_bf16_f32 v17, v18, v19
	global_store_dwordx2 v[88:89], v[16:17], off offset:288
	s_waitcnt vmcnt(29)
	v_lshlrev_b32_e32 v16, 16, v216
	v_and_b32_e32 v17, 0xffff0000, v216
	v_pk_mul_f32 v[12:13], v[12:13], v[16:17]
	v_lshlrev_b32_e32 v16, 16, v217
	v_and_b32_e32 v17, 0xffff0000, v217
	v_pk_mul_f32 v[14:15], v[14:15], v[16:17]
	v_cvt_pk_bf16_f32 v12, v12, v13
	v_cvt_pk_bf16_f32 v13, v14, v15
	global_store_dwordx2 v[46:47], v[12:13], off offset:256
	v_lshlrev_b32_e32 v12, 16, v218
	v_and_b32_e32 v13, 0xffff0000, v218
	v_pk_mul_f32 v[8:9], v[8:9], v[12:13]
	v_lshlrev_b32_e32 v12, 16, v219
	v_and_b32_e32 v13, 0xffff0000, v219
	v_pk_mul_f32 v[10:11], v[10:11], v[12:13]
	v_cvt_pk_bf16_f32 v8, v8, v9
	v_cvt_pk_bf16_f32 v9, v10, v11
	global_store_dwordx2 v[46:47], v[8:9], off offset:288
	s_waitcnt vmcnt(30)
	v_lshlrev_b32_e32 v8, 16, v220
	v_and_b32_e32 v9, 0xffff0000, v220
	v_pk_mul_f32 v[4:5], v[4:5], v[8:9]
	v_lshlrev_b32_e32 v8, 16, v221
	v_and_b32_e32 v9, 0xffff0000, v221
	v_pk_mul_f32 v[6:7], v[6:7], v[8:9]
	v_cvt_pk_bf16_f32 v4, v4, v5
	v_cvt_pk_bf16_f32 v5, v6, v7
	global_store_dwordx2 v[38:39], v[4:5], off offset:256
	v_lshlrev_b32_e32 v4, 16, v222
	v_and_b32_e32 v5, 0xffff0000, v222
	v_pk_mul_f32 v[0:1], v[0:1], v[4:5]
	v_lshlrev_b32_e32 v4, 16, v223
	v_and_b32_e32 v5, 0xffff0000, v223
	v_pk_mul_f32 v[2:3], v[2:3], v[4:5]
	v_cvt_pk_bf16_f32 v0, v0, v1
	v_cvt_pk_bf16_f32 v1, v2, v3
	global_store_dwordx2 v[38:39], v[0:1], off offset:288
	s_andn2_b64 vcc, exec, s[46:47]
	s_add_i32 s92, s92, s3
	s_cbranch_vccz .LBB0_570
